# K2: K-loop LDS-DMA loads take their lane-offset VGPR directly (16 v_mov fewer per iteration), per-phase byte length kept by a skipped pad; on top of F1+K1
# baseline (speedup 1.0000x reference)
; #define PG8_STAGE(bufoff, gbase, voff) do { _Pragma("unroll") for (int _i = 0; _i < 2; ++_i) { unsigned _vo = (voff)[_i]; asm volatile("" : "+v"(_vo));   \
;         __builtin_amdgcn_global_load_lds((const unsigned*)((const char*)(gbase) + _vo), (LAS unsigned*)(lds + (bufoff) + ldsw + _i * 8192), 16, 0, 0); } } while (0)
; #define PG8_LDA(dst, b, h) do { _Pragma("unroll") for (int m = 0; m < 4; ++m) _Pragma("unroll") for (int k = 0; k < 2; ++k) dst[m][k] = *(const LAS bf16x8*)(lds + PG8_SA(b, h) + aoff + m * 2048 + k * 1024); } while (0)
; #define PG8_LDB(dst, b, h) do { _Pragma("unroll") for (int n = 0; n < 2; ++n) _Pragma("unroll") for (int k = 0; k < 2; ++k) dst[n][k] = *(const LAS bf16x8*)(lds + PG8_SB(b, h) + boff + n * 2048 + k * 1024); } while (0)
; #define PG8_MMA(ai, bj, At, Bt) do { __builtin_amdgcn_s_setprio(1); _Pragma("unroll") for (int m = 0; m < 4; ++m) _Pragma("unroll") for (int n = 0; n < 2; ++n) _Pragma("unroll") for (int k = 0; k < 2; ++k) \
;         acc[ai][bj][m][n] = __builtin_amdgcn_mfma_f32_16x16x32_bf16(Bt[n][k], At[m][k], acc[ai][bj][m][n], 0, 0, 0); __builtin_amdgcn_s_setprio(0); } while (0)
; #define PG8_WAIT_V(n) asm volatile("s_waitcnt vmcnt(" #n ")" ::: "memory")
; #define PG8_WAIT_L(n) asm volatile("s_waitcnt lgkmcnt(" #n ")" ::: "memory")
; #define PG8_BAR __builtin_amdgcn_s_barrier()
; __device__ __forceinline__ void gemm_phase(LAS unsigned char* lds, const Call& C, const int tid, const Args& args) {
;     ...
;         const int nt = 2 * cur.np;
;         for (int t = 0; t < nt; t += 2) {
;             const bool last = (t == nt - 2);
;             const char* a1 = cA + (size_t)(t + 1) * kstep;
;             const char* a2 = last ? nA : cA + (size_t)(t + 2) * kstep; const char* b2 = last ? nB : cB + (size_t)(t + 2) * kstep;
;             const char* a3 = a2 + kstep; const char* b3 = b2 + kstep;
;             PG8_LDB(B0, 0, 0); PG8_LDB(B1, 0, 1); PG8_SCHED; PG8_LDA(At, 0, 0); PG8_STAGE(PG8_SA(1, 1), a1 + hstepA, voffA);
;             PG8_WAIT_V(8); PG8_WAIT_L(0); PG8_BAR; PG8_MMA(0, 0, At, B0); PG8_MMA(0, 1, At, B1); PG8_BAR; PG8_SCHED;
;             PG8_LDA(At, 0, 1); PG8_STAGE(PG8_SB(0, 0), b2, voffB); PG8_STAGE(PG8_SB(0, 1), b2 + hstepB, voffB); PG8_STAGE(PG8_SA(0, 0), a2, voffA);
;             PG8_WAIT_V(8); PG8_WAIT_L(0); PG8_BAR; PG8_MMA(1, 0, At, B0); PG8_MMA(1, 1, At, B1); PG8_BAR; PG8_SCHED;
.Lnu_noprod:
	s_cmp_eq_u32 s16, 0
	s_cbranch_scc1 .LBB0_313
	s_lshl_b32 s12, s16, 1
	s_add_i32 s13, s12, -2
	s_add_u32 s16, s8, 0x100
	s_addc_u32 s17, s9, 0
	s_mov_b32 s24, 0
	s_waitcnt lgkmcnt(0)
	s_add_i32 s25, s24, 2
	s_add_u32 s8, s0, 0x100
	s_addc_u32 s9, s1, 0
	s_add_i32 s34, 0, 0x10000
	s_cmp_eq_u32 s13, s24
	s_cselect_b32 s39, s87, s9
	s_cselect_b32 s38, s86, s8
	v_add_u32_e32 v80, s34, v245
	s_cselect_b32 s41, s49, s17
	s_cselect_b32 s40, s48, s16
	s_add_i32 s24, 0, 0x14000
	ds_read_b128 v[136:139], v80
	ds_read_b128 v[140:143], v80 offset:1024
	ds_read_b128 v[144:147], v80 offset:2048
	ds_read_b128 v[148:151], v80 offset:3072
	v_add_u32_e32 v80, s24, v245
	ds_read_b128 v[152:155], v80
	ds_read_b128 v[156:159], v80 offset:1024
	ds_read_b128 v[160:163], v80 offset:2048
	ds_read_b128 v[164:167], v80 offset:3072
	s_add_u32 s0, s0, s89
	ds_read_b128 v[168:171], v246
	ds_read_b128 v[172:175], v246 offset:1024
	ds_read_b128 v[176:179], v246 offset:2048
	ds_read_b128 v[180:183], v246 offset:3072
	ds_read_b128 v[184:187], v246 offset:4096
	ds_read_b128 v[188:191], v246 offset:5120
	ds_read_b128 v[192:195], v246 offset:6144
	ds_read_b128 v[196:199], v246 offset:7168
	s_addc_u32 s1, s1, s94
	s_add_i32 m0, s20, 0xc000
	s_nop 0
	global_load_lds_dwordx4 v205, s[0:1]
	s_add_i32 m0, s20, 0xe000
	s_nop 0
	global_load_lds_dwordx4 v243, s[0:1]
	s_branch .Lk2_6
	s_nop 0
.Lk2_6:
	s_waitcnt vmcnt(8)
	s_waitcnt lgkmcnt(0)
	s_barrier
	s_setprio 1
	s_waitcnt lgkmcnt(0)
	v_mfma_f32_16x16x32_bf16 v[132:135], v[136:139], v[168:171], 0
	v_mfma_f32_16x16x32_bf16 v[128:131], v[144:147], v[168:171], 0
	v_mfma_f32_16x16x32_bf16 v[124:127], v[136:139], v[176:179], 0
	v_mfma_f32_16x16x32_bf16 v[120:123], v[144:147], v[176:179], 0
	v_mfma_f32_16x16x32_bf16 v[108:111], v[136:139], v[184:187], 0
	v_mfma_f32_16x16x32_bf16 v[104:107], v[144:147], v[184:187], 0
	v_mfma_f32_16x16x32_bf16 v[92:95], v[136:139], v[192:195], 0
	v_mfma_f32_16x16x32_bf16 v[86:89], v[144:147], v[192:195], 0
	v_mfma_f32_16x16x32_bf16 v[132:135], v[140:143], v[172:175], v[132:135]
	v_mfma_f32_16x16x32_bf16 v[128:131], v[148:151], v[172:175], v[128:131]
	v_mfma_f32_16x16x32_bf16 v[124:127], v[140:143], v[180:183], v[124:127]
	v_mfma_f32_16x16x32_bf16 v[120:123], v[148:151], v[180:183], v[120:123]
	v_mfma_f32_16x16x32_bf16 v[108:111], v[140:143], v[188:191], v[108:111]
	v_mfma_f32_16x16x32_bf16 v[104:107], v[148:151], v[188:191], v[104:107]
	v_mfma_f32_16x16x32_bf16 v[92:95], v[140:143], v[196:199], v[92:95]
	v_mfma_f32_16x16x32_bf16 v[86:89], v[148:151], v[196:199], v[86:89]
	s_setprio 0
	s_setprio 1
	v_mfma_f32_16x16x32_bf16 v[116:119], v[152:155], v[168:171], 0
	v_mfma_f32_16x16x32_bf16 v[112:115], v[160:163], v[168:171], 0
	v_mfma_f32_16x16x32_bf16 v[100:103], v[152:155], v[176:179], 0
	v_mfma_f32_16x16x32_bf16 v[96:99], v[160:163], v[176:179], 0
	v_mfma_f32_16x16x32_bf16 v[76:79], v[152:155], v[184:187], 0
	v_mfma_f32_16x16x32_bf16 v[72:75], v[160:163], v[184:187], 0
	v_mfma_f32_16x16x32_bf16 v[68:71], v[152:155], v[192:195], 0
	v_mfma_f32_16x16x32_bf16 v[60:63], v[160:163], v[192:195], 0
	v_mfma_f32_16x16x32_bf16 v[116:119], v[156:159], v[172:175], v[116:119]
	v_mfma_f32_16x16x32_bf16 v[112:115], v[164:167], v[172:175], v[112:115]
	v_mfma_f32_16x16x32_bf16 v[100:103], v[156:159], v[180:183], v[100:103]
	v_mfma_f32_16x16x32_bf16 v[96:99], v[164:167], v[180:183], v[96:99]
	v_mfma_f32_16x16x32_bf16 v[76:79], v[156:159], v[188:191], v[76:79]
	v_mfma_f32_16x16x32_bf16 v[72:75], v[164:167], v[188:191], v[72:75]
	v_mfma_f32_16x16x32_bf16 v[68:71], v[156:159], v[196:199], v[68:71]
	v_mfma_f32_16x16x32_bf16 v[60:63], v[164:167], v[196:199], v[60:63]
	s_setprio 0
	s_barrier
	s_add_i32 s0, s34, s23
	ds_read_b128 v[168:171], v246 offset:16384
	ds_read_b128 v[172:175], v246 offset:17408
	ds_read_b128 v[176:179], v246 offset:18432
	ds_read_b128 v[180:183], v246 offset:19456
	ds_read_b128 v[184:187], v246 offset:20480
	ds_read_b128 v[188:191], v246 offset:21504
	ds_read_b128 v[192:195], v246 offset:22528
	ds_read_b128 v[196:199], v246 offset:23552
	s_mov_b32 m0, s0
	s_nop 0
	global_load_lds_dwordx4 v242, s[40:41]
	s_add_i32 m0, s0, 0x2000
	s_add_u32 s0, s40, s74
	global_load_lds_dwordx4 v244, s[40:41]
	s_addc_u32 s1, s41, s75
	s_add_i32 s24, s24, s23
	s_mov_b32 m0, s24
	s_nop 0
	global_load_lds_dwordx4 v242, s[0:1]
	s_add_i32 m0, s24, 0x2000
	s_nop 0
	global_load_lds_dwordx4 v244, s[0:1]
	s_mov_b32 m0, s20
	s_nop 0
	global_load_lds_dwordx4 v205, s[38:39]
	s_mov_b32 m0, s72
	s_nop 0
	global_load_lds_dwordx4 v243, s[38:39]
	s_branch .Lk2_5
	s_nop 0
	s_nop 0
	s_nop 0
	s_nop 0
	s_nop 0
.Lk2_5:
	s_waitcnt vmcnt(8)
	s_waitcnt lgkmcnt(0)
	s_barrier
	s_setprio 1
	s_waitcnt lgkmcnt(0)
	v_mfma_f32_16x16x32_bf16 v[64:67], v[136:139], v[168:171], 0
	v_mfma_f32_16x16x32_bf16 v[56:59], v[144:147], v[168:171], 0
	v_mfma_f32_16x16x32_bf16 v[52:55], v[136:139], v[176:179], 0
	v_mfma_f32_16x16x32_bf16 v[48:51], v[144:147], v[176:179], 0
	v_mfma_f32_16x16x32_bf16 v[36:39], v[136:139], v[184:187], 0
	v_mfma_f32_16x16x32_bf16 v[32:35], v[144:147], v[184:187], 0
	v_mfma_f32_16x16x32_bf16 v[20:23], v[136:139], v[192:195], 0
	v_mfma_f32_16x16x32_bf16 v[16:19], v[144:147], v[192:195], 0
	v_mfma_f32_16x16x32_bf16 v[64:67], v[140:143], v[172:175], v[64:67]
	v_mfma_f32_16x16x32_bf16 v[56:59], v[148:151], v[172:175], v[56:59]
	v_mfma_f32_16x16x32_bf16 v[52:55], v[140:143], v[180:183], v[52:55]
	v_mfma_f32_16x16x32_bf16 v[48:51], v[148:151], v[180:183], v[48:51]
	v_mfma_f32_16x16x32_bf16 v[36:39], v[140:143], v[188:191], v[36:39]
	v_mfma_f32_16x16x32_bf16 v[32:35], v[148:151], v[188:191], v[32:35]
	v_mfma_f32_16x16x32_bf16 v[20:23], v[140:143], v[196:199], v[20:23]
	v_mfma_f32_16x16x32_bf16 v[16:19], v[148:151], v[196:199], v[16:19]
	s_setprio 0
	s_setprio 1
	v_mfma_f32_16x16x32_bf16 v[44:47], v[152:155], v[168:171], 0
	v_mfma_f32_16x16x32_bf16 v[40:43], v[160:163], v[168:171], 0
	v_mfma_f32_16x16x32_bf16 v[28:31], v[152:155], v[176:179], 0
	v_mfma_f32_16x16x32_bf16 v[24:27], v[160:163], v[176:179], 0
	v_mfma_f32_16x16x32_bf16 v[12:15], v[152:155], v[184:187], 0
	v_mfma_f32_16x16x32_bf16 v[8:11], v[160:163], v[184:187], 0
	v_mfma_f32_16x16x32_bf16 v[4:7], v[152:155], v[192:195], 0
	v_mfma_f32_16x16x32_bf16 v[0:3], v[160:163], v[192:195], 0
	v_mfma_f32_16x16x32_bf16 v[44:47], v[156:159], v[172:175], v[44:47]
	v_mfma_f32_16x16x32_bf16 v[40:43], v[164:167], v[172:175], v[40:43]
	v_mfma_f32_16x16x32_bf16 v[28:31], v[156:159], v[180:183], v[28:31]
	v_mfma_f32_16x16x32_bf16 v[24:27], v[164:167], v[180:183], v[24:27]
	v_mfma_f32_16x16x32_bf16 v[12:15], v[156:159], v[188:191], v[12:15]
	v_mfma_f32_16x16x32_bf16 v[8:11], v[164:167], v[188:191], v[8:11]
	v_mfma_f32_16x16x32_bf16 v[4:7], v[156:159], v[196:199], v[4:7]
	v_mfma_f32_16x16x32_bf16 v[0:3], v[164:167], v[196:199], v[0:3]
	s_setprio 0
	s_barrier
	s_branch .Lp7_ph3

; #define PG8_STAGE(bufoff, gbase, voff) do { _Pragma("unroll") for (int _i = 0; _i < 2; ++_i) { unsigned _vo = (voff)[_i]; asm volatile("" : "+v"(_vo));   \
;         __builtin_amdgcn_global_load_lds((const unsigned*)((const char*)(gbase) + _vo), (LAS unsigned*)(lds + (bufoff) + ldsw + _i * 8192), 16, 0, 0); } } while (0)
; #define PG8_LDA(dst, b, h) do { _Pragma("unroll") for (int m = 0; m < 4; ++m) _Pragma("unroll") for (int k = 0; k < 2; ++k) dst[m][k] = *(const LAS bf16x8*)(lds + PG8_SA(b, h) + aoff + m * 2048 + k * 1024); } while (0)
; #define PG8_LDB(dst, b, h) do { _Pragma("unroll") for (int n = 0; n < 2; ++n) _Pragma("unroll") for (int k = 0; k < 2; ++k) dst[n][k] = *(const LAS bf16x8*)(lds + PG8_SB(b, h) + boff + n * 2048 + k * 1024); } while (0)
; #define PG8_MMA(ai, bj, At, Bt) do { __builtin_amdgcn_s_setprio(1); _Pragma("unroll") for (int m = 0; m < 4; ++m) _Pragma("unroll") for (int n = 0; n < 2; ++n) _Pragma("unroll") for (int k = 0; k < 2; ++k) \
;         acc[ai][bj][m][n] = __builtin_amdgcn_mfma_f32_16x16x32_bf16(Bt[n][k], At[m][k], acc[ai][bj][m][n], 0, 0, 0); __builtin_amdgcn_s_setprio(0); } while (0)
; #define PG8_WAIT_V(n) asm volatile("s_waitcnt vmcnt(" #n ")" ::: "memory")
; #define PG8_WAIT_L(n) asm volatile("s_waitcnt lgkmcnt(" #n ")" ::: "memory")
; #define PG8_BAR __builtin_amdgcn_s_barrier()
; #define PG8_SCHED __builtin_amdgcn_sched_barrier(0)
; __device__ __forceinline__ void gemm_phase(LAS unsigned char* lds, const Call& C, const int tid, const Args& args) {
;     ...
;         for (int t = 0; t < nt; t += 2) {
;             const bool last = (t == nt - 2);
;             const char* a1 = cA + (size_t)(t + 1) * kstep;
;             const char* a2 = last ? nA : cA + (size_t)(t + 2) * kstep; const char* b2 = last ? nB : cB + (size_t)(t + 2) * kstep;
;             const char* a3 = a2 + kstep; const char* b3 = b2 + kstep;
;             PG8_LDB(B0, 0, 0); PG8_LDB(B1, 0, 1); PG8_SCHED; PG8_LDA(At, 0, 0); PG8_STAGE(PG8_SA(1, 1), a1 + hstepA, voffA);
;             PG8_WAIT_V(8); PG8_WAIT_L(0); PG8_BAR; PG8_MMA(0, 0, At, B0); PG8_MMA(0, 1, At, B1); PG8_BAR; PG8_SCHED;
;             PG8_LDA(At, 0, 1); PG8_STAGE(PG8_SB(0, 0), b2, voffB); PG8_STAGE(PG8_SB(0, 1), b2 + hstepB, voffB); PG8_STAGE(PG8_SA(0, 0), a2, voffA);
;             PG8_WAIT_V(8); PG8_WAIT_L(0); PG8_BAR; PG8_MMA(1, 0, At, B0); PG8_MMA(1, 1, At, B1); PG8_BAR; PG8_SCHED;
.Lnu_nofetch:
	s_add_i32 s25, s24, 2
	s_add_u32 s8, s0, 0x100
	s_addc_u32 s9, s1, 0
	s_add_i32 s34, 0, 0x10000
	s_cmp_eq_u32 s13, s24
	s_cselect_b32 s39, s87, s9
	s_cselect_b32 s38, s86, s8
	v_add_u32_e32 v80, s34, v245
	s_cselect_b32 s41, s49, s17
	s_cselect_b32 s40, s48, s16
	s_add_i32 s24, 0, 0x14000
	ds_read_b128 v[136:139], v80
	ds_read_b128 v[140:143], v80 offset:1024
	ds_read_b128 v[144:147], v80 offset:2048
	ds_read_b128 v[148:151], v80 offset:3072
	v_add_u32_e32 v80, s24, v245
	ds_read_b128 v[152:155], v80
	ds_read_b128 v[156:159], v80 offset:1024
	ds_read_b128 v[160:163], v80 offset:2048
	ds_read_b128 v[164:167], v80 offset:3072
	s_add_u32 s0, s0, s89
	ds_read_b128 v[168:171], v246
	ds_read_b128 v[172:175], v246 offset:1024
	ds_read_b128 v[176:179], v246 offset:2048
	ds_read_b128 v[180:183], v246 offset:3072
	ds_read_b128 v[184:187], v246 offset:4096
	ds_read_b128 v[188:191], v246 offset:5120
	ds_read_b128 v[192:195], v246 offset:6144
	ds_read_b128 v[196:199], v246 offset:7168
	s_addc_u32 s1, s1, s94
	s_add_i32 m0, s20, 0xc000
	s_nop 0
	global_load_lds_dwordx4 v205, s[0:1]
	s_add_i32 m0, s20, 0xe000
	s_nop 0
	global_load_lds_dwordx4 v243, s[0:1]
	s_branch .Lk2_4
	s_nop 0
.Lk2_4:
	s_waitcnt vmcnt(8)
	s_waitcnt lgkmcnt(0)
	s_barrier
	s_setprio 1
	s_waitcnt lgkmcnt(0)
	v_mfma_f32_16x16x32_bf16 v[132:135], v[136:139], v[168:171], v[132:135]
	v_mfma_f32_16x16x32_bf16 v[128:131], v[144:147], v[168:171], v[128:131]
	v_mfma_f32_16x16x32_bf16 v[124:127], v[136:139], v[176:179], v[124:127]
	v_mfma_f32_16x16x32_bf16 v[120:123], v[144:147], v[176:179], v[120:123]
	v_mfma_f32_16x16x32_bf16 v[108:111], v[136:139], v[184:187], v[108:111]
	v_mfma_f32_16x16x32_bf16 v[104:107], v[144:147], v[184:187], v[104:107]
	v_mfma_f32_16x16x32_bf16 v[92:95], v[136:139], v[192:195], v[92:95]
	v_mfma_f32_16x16x32_bf16 v[86:89], v[144:147], v[192:195], v[88:91]
	v_mfma_f32_16x16x32_bf16 v[132:135], v[140:143], v[172:175], v[132:135]
	v_mfma_f32_16x16x32_bf16 v[128:131], v[148:151], v[172:175], v[128:131]
	v_mfma_f32_16x16x32_bf16 v[124:127], v[140:143], v[180:183], v[124:127]
	v_mfma_f32_16x16x32_bf16 v[120:123], v[148:151], v[180:183], v[120:123]
	v_mfma_f32_16x16x32_bf16 v[108:111], v[140:143], v[188:191], v[108:111]
	v_mfma_f32_16x16x32_bf16 v[104:107], v[148:151], v[188:191], v[104:107]
	v_mfma_f32_16x16x32_bf16 v[92:95], v[140:143], v[196:199], v[92:95]
	v_mfma_f32_16x16x32_bf16 v[86:89], v[148:151], v[196:199], v[86:89]
	s_setprio 0
	s_setprio 1
	v_mfma_f32_16x16x32_bf16 v[116:119], v[152:155], v[168:171], v[116:119]
	v_mfma_f32_16x16x32_bf16 v[112:115], v[160:163], v[168:171], v[112:115]
	v_mfma_f32_16x16x32_bf16 v[100:103], v[152:155], v[176:179], v[100:103]
	v_mfma_f32_16x16x32_bf16 v[96:99], v[160:163], v[176:179], v[96:99]
	v_mfma_f32_16x16x32_bf16 v[76:79], v[152:155], v[184:187], v[76:79]
	v_mfma_f32_16x16x32_bf16 v[72:75], v[160:163], v[184:187], v[72:75]
	v_mfma_f32_16x16x32_bf16 v[68:71], v[152:155], v[192:195], v[68:71]
	v_mfma_f32_16x16x32_bf16 v[60:63], v[160:163], v[192:195], v[60:63]
	v_mfma_f32_16x16x32_bf16 v[116:119], v[156:159], v[172:175], v[116:119]
	v_mfma_f32_16x16x32_bf16 v[112:115], v[164:167], v[172:175], v[112:115]
	v_mfma_f32_16x16x32_bf16 v[100:103], v[156:159], v[180:183], v[100:103]
	v_mfma_f32_16x16x32_bf16 v[96:99], v[164:167], v[180:183], v[96:99]
	v_mfma_f32_16x16x32_bf16 v[76:79], v[156:159], v[188:191], v[76:79]
	v_mfma_f32_16x16x32_bf16 v[72:75], v[164:167], v[188:191], v[72:75]
	v_mfma_f32_16x16x32_bf16 v[68:71], v[156:159], v[196:199], v[68:71]
	v_mfma_f32_16x16x32_bf16 v[60:63], v[164:167], v[196:199], v[60:63]
	s_setprio 0
	s_barrier
	s_add_i32 s0, s34, s23
	ds_read_b128 v[168:171], v246 offset:16384
	ds_read_b128 v[172:175], v246 offset:17408
	ds_read_b128 v[176:179], v246 offset:18432
	ds_read_b128 v[180:183], v246 offset:19456
	ds_read_b128 v[184:187], v246 offset:20480
	ds_read_b128 v[188:191], v246 offset:21504
	ds_read_b128 v[192:195], v246 offset:22528
	ds_read_b128 v[196:199], v246 offset:23552
	s_mov_b32 m0, s0
	s_nop 0
	global_load_lds_dwordx4 v242, s[40:41]
	s_add_i32 m0, s0, 0x2000
	s_add_u32 s0, s40, s74
	global_load_lds_dwordx4 v244, s[40:41]
	s_addc_u32 s1, s41, s75
	s_add_i32 s24, s24, s23
	s_mov_b32 m0, s24
	s_nop 0
	global_load_lds_dwordx4 v242, s[0:1]
	s_add_i32 m0, s24, 0x2000
	s_nop 0
	global_load_lds_dwordx4 v244, s[0:1]
	s_mov_b32 m0, s20
	s_nop 0
	global_load_lds_dwordx4 v205, s[38:39]
	s_mov_b32 m0, s72
	s_nop 0
	global_load_lds_dwordx4 v243, s[38:39]
	s_branch .Lk2_3
	s_nop 0
	s_nop 0
	s_nop 0
	s_nop 0
	s_nop 0

; #define PG8_STAGE(bufoff, gbase, voff) do { _Pragma("unroll") for (int _i = 0; _i < 2; ++_i) { unsigned _vo = (voff)[_i]; asm volatile("" : "+v"(_vo));   \
;         __builtin_amdgcn_global_load_lds((const unsigned*)((const char*)(gbase) + _vo), (LAS unsigned*)(lds + (bufoff) + ldsw + _i * 8192), 16, 0, 0); } } while (0)
; #define PG8_LDA(dst, b, h) do { _Pragma("unroll") for (int m = 0; m < 4; ++m) _Pragma("unroll") for (int k = 0; k < 2; ++k) dst[m][k] = *(const LAS bf16x8*)(lds + PG8_SA(b, h) + aoff + m * 2048 + k * 1024); } while (0)
; #define PG8_LDB(dst, b, h) do { _Pragma("unroll") for (int n = 0; n < 2; ++n) _Pragma("unroll") for (int k = 0; k < 2; ++k) dst[n][k] = *(const LAS bf16x8*)(lds + PG8_SB(b, h) + boff + n * 2048 + k * 1024); } while (0)
; #define PG8_MMA(ai, bj, At, Bt) do { __builtin_amdgcn_s_setprio(1); _Pragma("unroll") for (int m = 0; m < 4; ++m) _Pragma("unroll") for (int n = 0; n < 2; ++n) _Pragma("unroll") for (int k = 0; k < 2; ++k) \
;         acc[ai][bj][m][n] = __builtin_amdgcn_mfma_f32_16x16x32_bf16(Bt[n][k], At[m][k], acc[ai][bj][m][n], 0, 0, 0); __builtin_amdgcn_s_setprio(0); } while (0)
; #define PG8_WAIT_V(n) asm volatile("s_waitcnt vmcnt(" #n ")" ::: "memory")
; #define PG8_WAIT_L(n) asm volatile("s_waitcnt lgkmcnt(" #n ")" ::: "memory")
; #define PG8_BAR __builtin_amdgcn_s_barrier()
; #define PG8_SCHED __builtin_amdgcn_sched_barrier(0)
; __device__ __forceinline__ void gemm_phase(LAS unsigned char* lds, const Call& C, const int tid, const Args& args) {
;     ...
;             PG8_LDB(B0, 1, 0); PG8_LDB(B1, 1, 1); PG8_SCHED; PG8_LDA(At, 1, 0); PG8_STAGE(PG8_SA(0, 1), a2 + hstepA, voffA);
;             PG8_WAIT_V(8); PG8_WAIT_L(0); PG8_BAR; PG8_MMA(0, 0, At, B0); PG8_MMA(0, 1, At, B1); PG8_BAR; PG8_SCHED;
;             PG8_LDA(At, 1, 1); PG8_STAGE(PG8_SB(1, 0), b3, voffB); PG8_STAGE(PG8_SB(1, 1), b3 + hstepB, voffB); PG8_STAGE(PG8_SA(1, 0), a3, voffA);
;             PG8_WAIT_V(8); PG8_WAIT_L(0); PG8_BAR; PG8_MMA(1, 0, At, B0); PG8_MMA(1, 1, At, B1); PG8_BAR; PG8_SCHED;
.Lp7_ph3:
	s_add_i32 s24, 0, 0x18000
	v_add_u32_e32 v80, s24, v245
	s_add_i32 s42, 0, 0x1c000
	ds_read_b128 v[136:139], v80
	ds_read_b128 v[140:143], v80 offset:1024
	ds_read_b128 v[144:147], v80 offset:2048
	ds_read_b128 v[148:151], v80 offset:3072
	v_add_u32_e32 v80, s42, v245
	ds_read_b128 v[152:155], v80
	ds_read_b128 v[156:159], v80 offset:1024
	ds_read_b128 v[160:163], v80 offset:2048
	ds_read_b128 v[164:167], v80 offset:3072
	s_add_u32 s34, s38, s22
	s_mov_b32 m0, s73
	ds_read_b128 v[168:171], v246 offset:32768
	ds_read_b128 v[172:175], v246 offset:33792
	ds_read_b128 v[176:179], v246 offset:34816
	ds_read_b128 v[180:183], v246 offset:35840
	ds_read_b128 v[184:187], v246 offset:36864
	ds_read_b128 v[188:191], v246 offset:37888
	ds_read_b128 v[192:195], v246 offset:38912
	ds_read_b128 v[196:199], v246 offset:39936
	s_addc_u32 s35, s39, 0
	s_nop 0
	global_load_lds_dwordx4 v205, s[34:35]
	s_mov_b32 m0, s4
	s_nop 0
	global_load_lds_dwordx4 v243, s[34:35]
	s_branch .Lk2_2
	s_nop 0
.Lk2_2:
	s_waitcnt vmcnt(8)
	s_waitcnt lgkmcnt(0)
	s_barrier
	s_setprio 1
	s_waitcnt lgkmcnt(0)
	v_mfma_f32_16x16x32_bf16 v[132:135], v[136:139], v[168:171], v[132:135]
	v_mfma_f32_16x16x32_bf16 v[128:131], v[144:147], v[168:171], v[128:131]
	v_mfma_f32_16x16x32_bf16 v[124:127], v[136:139], v[176:179], v[124:127]
	v_mfma_f32_16x16x32_bf16 v[120:123], v[144:147], v[176:179], v[120:123]
	v_mfma_f32_16x16x32_bf16 v[108:111], v[136:139], v[184:187], v[108:111]
	v_mfma_f32_16x16x32_bf16 v[104:107], v[144:147], v[184:187], v[104:107]
	v_mfma_f32_16x16x32_bf16 v[90:93], v[136:139], v[192:195], v[92:95]
	v_mfma_f32_16x16x32_bf16 v[86:89], v[144:147], v[192:195], v[86:89]
	v_mfma_f32_16x16x32_bf16 v[132:135], v[140:143], v[172:175], v[132:135]
	v_mfma_f32_16x16x32_bf16 v[128:131], v[148:151], v[172:175], v[128:131]
	v_mfma_f32_16x16x32_bf16 v[124:127], v[140:143], v[180:183], v[124:127]
	v_mfma_f32_16x16x32_bf16 v[120:123], v[148:151], v[180:183], v[120:123]
	v_mfma_f32_16x16x32_bf16 v[108:111], v[140:143], v[188:191], v[108:111]
	v_mfma_f32_16x16x32_bf16 v[104:107], v[148:151], v[188:191], v[104:107]
	v_mfma_f32_16x16x32_bf16 v[92:95], v[140:143], v[196:199], v[90:93]
	v_mfma_f32_16x16x32_bf16 v[88:91], v[148:151], v[196:199], v[86:89]
	s_setprio 0
	s_setprio 1
	v_mfma_f32_16x16x32_bf16 v[116:119], v[152:155], v[168:171], v[116:119]
	v_mfma_f32_16x16x32_bf16 v[112:115], v[160:163], v[168:171], v[112:115]
	v_mfma_f32_16x16x32_bf16 v[100:103], v[152:155], v[176:179], v[100:103]
	v_mfma_f32_16x16x32_bf16 v[96:99], v[160:163], v[176:179], v[96:99]
	v_mfma_f32_16x16x32_bf16 v[76:79], v[152:155], v[184:187], v[76:79]
	v_mfma_f32_16x16x32_bf16 v[72:75], v[160:163], v[184:187], v[72:75]
	v_mfma_f32_16x16x32_bf16 v[68:71], v[152:155], v[192:195], v[68:71]
	v_mfma_f32_16x16x32_bf16 v[60:63], v[160:163], v[192:195], v[60:63]
	v_mfma_f32_16x16x32_bf16 v[116:119], v[156:159], v[172:175], v[116:119]
	v_mfma_f32_16x16x32_bf16 v[112:115], v[164:167], v[172:175], v[112:115]
	v_mfma_f32_16x16x32_bf16 v[100:103], v[156:159], v[180:183], v[100:103]
	v_mfma_f32_16x16x32_bf16 v[96:99], v[164:167], v[180:183], v[96:99]
	v_mfma_f32_16x16x32_bf16 v[76:79], v[156:159], v[188:191], v[76:79]
	v_mfma_f32_16x16x32_bf16 v[72:75], v[164:167], v[188:191], v[72:75]
	v_mfma_f32_16x16x32_bf16 v[68:71], v[156:159], v[196:199], v[68:71]
	v_mfma_f32_16x16x32_bf16 v[60:63], v[164:167], v[196:199], v[60:63]
	s_setprio 0
	s_barrier
	ds_read_b128 v[168:171], v246 offset:49152
	ds_read_b128 v[172:175], v246 offset:50176
	ds_read_b128 v[176:179], v246 offset:51200
	ds_read_b128 v[180:183], v246 offset:52224
	ds_read_b128 v[184:187], v246 offset:53248
	ds_read_b128 v[188:191], v246 offset:54272
	ds_read_b128 v[192:195], v246 offset:55296
	ds_read_b128 v[196:199], v246 offset:56320
	s_add_i32 s24, s24, s23
	s_add_u32 vcc_lo, s40, s18
	s_addc_u32 vcc_hi, s41, s19
	s_mov_b32 m0, s24
	s_nop 0
	global_load_lds_dwordx4 v242, vcc
	s_add_i32 m0, s24, 0x2000
	s_nop 0
	global_load_lds_dwordx4 v244, vcc
	s_add_i32 s24, s42, s23
	s_add_u32 vcc_lo, s0, s18
	s_addc_u32 vcc_hi, s1, s19
	s_mov_b32 m0, s24
	s_nop 0
	global_load_lds_dwordx4 v242, vcc
	s_add_i32 m0, s24, 0x2000
	s_nop 0
	global_load_lds_dwordx4 v244, vcc
	s_add_u32 vcc_lo, s38, s18
	s_addc_u32 vcc_hi, s39, s19
	s_mov_b32 m0, s14
	s_nop 0
	global_load_lds_dwordx4 v205, vcc
	s_mov_b32 m0, s52
	s_nop 0
	global_load_lds_dwordx4 v243, vcc
	s_branch .Lk1_over
	s_nop 0
	s_nop 0
	s_nop 0
	s_nop 0
	s_nop 0
	s_nop 0
	s_nop 0
	s_nop 0
	s_nop 0
	s_nop 0
	s_nop 0
.Lk1_over:
	s_branch .Lk2_1
	s_nop 0
	s_nop 0
	s_nop 0
	s_nop 0
	s_nop 0
